# v21 + down-projection epilogue: second half's 8 residual loads issued with the first half's on fresh registers (not queued behind the first half's 16 output stores)
# baseline (speedup 1.0000x reference)
;     __device__ __forceinline__ void operator()(const f32x4 (&acc)[2][2][4][2], const Unit& u, int wr, int wc, int fr, int fq) const {
;     ...
;         float* const yb = yp + (size_t)row0 * 1024;
; #pragma unroll
;         for (int ai = 0; ai < 2; ++ai) {
;             u32x4 xw[4][2];
; #pragma unroll
;             for (int m = 0; m < 4; ++m)
; #pragma unroll
;                 for (int bj = 0; bj < 2; ++bj) xw[m][bj] = *(const u32x4*)(X1B + (size_t)(row0 + ai * HALF + m * 16) * 1024 + col0 + bj * HALF);
; #pragma unroll
;             for (int m = 0; m < 4; ++m) {
;                 float* yo = yb + (size_t)(ai * HALF + m * 16) * 1024;
; #pragma unroll
;                 for (int bj = 0; bj < 2; ++bj) { float* p = yo + col0 + bj * HALF; const u32x4 w = xw[m][bj];
;                     *(f32x4*)p = (f32x4){__builtin_bit_cast(float, w.x << 16), __builtin_bit_cast(float, w.x & 0xffff0000u), __builtin_bit_cast(float, w.y << 16), __builtin_bit_cast(float, w.y & 0xffff0000u)} + acc[ai][bj][m][0];
;                     *(f32x4*)(p + 4) = (f32x4){__builtin_bit_cast(float, w.z << 16), __builtin_bit_cast(float, w.z & 0xffff0000u), __builtin_bit_cast(float, w.w << 16), __builtin_bit_cast(float, w.w & 0xffff0000u)} + acc[ai][bj][m][1]; }
.LBB0_1180:
	s_lshl_b32 s62, s85, 8
	v_mbcnt_lo_u32_b32 v130, -1, 0
	v_mbcnt_hi_u32_b32 v130, -1, v130
	s_add_i32 s62, s62, s60
	v_and_or_b32 v150, v130, 15, s62
	s_lshl_b32 s62, s86, 8
	v_ashrrev_i32_e32 v130, 1, v130
	v_and_b32_e32 v130, -8, v130
	s_or_b32 s62, s62, s61
	v_add_u32_e32 v152, s62, v130
	s_cmp_lt_i32 s85, 64
	s_mov_b64 s[62:63], -1
	s_cbranch_scc0 .LBB0_1183
	v_ashrrev_i32_e32 v151, 31, v150
	v_ashrrev_i32_e32 v153, 31, v152
	v_lshl_add_u64 v[130:131], v[152:153], 1, s[10:11]
	v_lshlrev_b64 v[132:133], 11, v[150:151]
	v_lshl_add_u64 v[156:157], v[130:131], 0, v[132:133]
	v_or_b32_e32 v132, 16, v150
	v_ashrrev_i32_e32 v133, 31, v132
	v_lshlrev_b64 v[132:133], 11, v[132:133]
	v_lshl_add_u64 v[132:133], v[130:131], 0, v[132:133]
	global_load_dwordx4 v[162:165], v[156:157], off
	global_load_dwordx4 v[166:169], v[156:157], off offset:256
	global_load_dwordx4 v[170:173], v[132:133], off
	global_load_dwordx4 v[174:177], v[132:133], off offset:256
	v_or_b32_e32 v132, 32, v150
	v_ashrrev_i32_e32 v133, 31, v132
	v_lshlrev_b64 v[132:133], 11, v[132:133]
	v_lshl_add_u64 v[132:133], v[130:131], 0, v[132:133]
	global_load_dwordx4 v[178:181], v[132:133], off
	v_or_b32_e32 v134, 48, v150
	v_ashrrev_i32_e32 v135, 31, v134
	v_lshlrev_b64 v[136:137], 12, v[150:151]
	v_lshlrev_b64 v[134:135], 11, v[134:135]
	v_lshl_add_u64 v[136:137], s[8:9], 0, v[136:137]
	v_lshl_add_u64 v[130:131], v[130:131], 0, v[134:135]
	v_lshl_add_u64 v[154:155], v[152:153], 2, v[136:137]
	global_load_dwordx4 v[182:185], v[132:133], off offset:256
	global_load_dwordx4 v[134:137], v[130:131], off
	s_nop 0
	global_load_dwordx4 v[130:133], v[130:131], off offset:256
	v_add_co_u32_e32 v236, vcc, s75, v156
	s_nop 1
	v_addc_co_u32_e32 v237, vcc, 0, v157, vcc
	global_load_dwordx4 v[204:207], v[236:237], off
	v_lshl_add_u64 v[236:237], v[156:157], 0, s[18:19]
	global_load_dwordx4 v[208:211], v[236:237], off offset:256
	v_add_co_u32_e32 v236, vcc, s76, v156
	s_nop 1
	v_addc_co_u32_e32 v237, vcc, 0, v157, vcc
	global_load_dwordx4 v[212:215], v[236:237], off
	v_lshl_add_u64 v[236:237], v[156:157], 0, s[20:21]
	global_load_dwordx4 v[216:219], v[236:237], off offset:256
	v_add_co_u32_e32 v236, vcc, s77, v156
	s_nop 1
	v_addc_co_u32_e32 v237, vcc, 0, v157, vcc
	global_load_dwordx4 v[220:223], v[236:237], off
	v_lshl_add_u64 v[236:237], v[156:157], 0, s[22:23]
	global_load_dwordx4 v[224:227], v[236:237], off offset:256
	v_add_co_u32_e32 v236, vcc, s78, v156
	s_nop 1
	v_addc_co_u32_e32 v237, vcc, 0, v157, vcc
	global_load_dwordx4 v[228:231], v[236:237], off
	v_lshl_add_u64 v[236:237], v[156:157], 0, s[24:25]
	global_load_dwordx4 v[232:235], v[236:237], off offset:256
	s_mov_b32 s62, 0x10000
	v_add_co_u32_e32 v194, vcc, s62, v154
	s_mov_b32 s62, 0x20000
	s_nop 0
	v_addc_co_u32_e32 v195, vcc, 0, v155, vcc
	s_waitcnt vmcnt(8)
	v_lshlrev_b32_e32 v186, 16, v162
	v_and_b32_e32 v187, 0xffff0000, v162
	v_lshlrev_b32_e32 v162, 16, v163
	v_and_b32_e32 v163, 0xffff0000, v163
	v_lshlrev_b32_e32 v188, 16, v164
	v_and_b32_e32 v189, 0xffff0000, v164
	v_lshlrev_b32_e32 v190, 16, v165
	v_and_b32_e32 v191, 0xffff0000, v165
	v_lshlrev_b32_e32 v196, 16, v167
	v_and_b32_e32 v197, 0xffff0000, v167
	v_lshlrev_b32_e32 v198, 16, v168
	v_and_b32_e32 v199, 0xffff0000, v168
	v_lshlrev_b32_e32 v192, 16, v166
	v_and_b32_e32 v193, 0xffff0000, v166
	v_lshlrev_b32_e32 v200, 16, v169
	v_and_b32_e32 v201, 0xffff0000, v169
	v_pk_add_f32 v[164:165], v[128:129], v[162:163]
	v_pk_add_f32 v[162:163], v[126:127], v[186:187]
	v_pk_add_f32 v[168:169], v[124:125], v[190:191]
	v_pk_add_f32 v[166:167], v[122:123], v[188:189]
	v_pk_add_f32 v[188:189], v[112:113], v[196:197]
	v_pk_add_f32 v[190:191], v[102:103], v[198:199]
	v_lshlrev_b32_e32 v196, 16, v170
	v_and_b32_e32 v197, 0xffff0000, v170
	v_lshlrev_b32_e32 v170, 16, v171
	v_and_b32_e32 v171, 0xffff0000, v171
	v_lshlrev_b32_e32 v198, 16, v172
	v_and_b32_e32 v199, 0xffff0000, v172
	v_pk_add_f32 v[186:187], v[110:111], v[192:193]
	v_pk_add_f32 v[192:193], v[104:105], v[200:201]
	v_lshlrev_b32_e32 v172, 16, v173
	v_and_b32_e32 v173, 0xffff0000, v173
	v_lshlrev_b32_e32 v200, 16, v174
	v_and_b32_e32 v201, 0xffff0000, v174
	v_lshlrev_b32_e32 v174, 16, v175
	v_and_b32_e32 v175, 0xffff0000, v175
	v_lshlrev_b32_e32 v202, 16, v176
	v_and_b32_e32 v203, 0xffff0000, v176
	v_lshlrev_b32_e32 v176, 16, v177
	v_and_b32_e32 v177, 0xffff0000, v177
	global_store_dwordx4 v[154:155], v[162:165], off
	global_store_dwordx4 v[154:155], v[166:169], off offset:16
	global_store_dwordx4 v[154:155], v[186:189], off offset:512
	global_store_dwordx4 v[154:155], v[190:193], off offset:528
	v_pk_add_f32 v[164:165], v[120:121], v[170:171]
	v_pk_add_f32 v[162:163], v[118:119], v[196:197]
	v_pk_add_f32 v[166:167], v[114:115], v[198:199]
	v_pk_add_f32 v[168:169], v[116:117], v[172:173]
	v_pk_add_f32 v[172:173], v[96:97], v[174:175]
	v_pk_add_f32 v[170:171], v[94:95], v[200:201]
	v_pk_add_f32 v[176:177], v[88:89], v[176:177]
	v_pk_add_f32 v[174:175], v[86:87], v[202:203]
	global_store_dwordx4 v[194:195], v[162:165], off
	global_store_dwordx4 v[194:195], v[166:169], off offset:16
	global_store_dwordx4 v[194:195], v[170:173], off offset:512
	global_store_dwordx4 v[194:195], v[174:177], off offset:528
	v_lshlrev_b32_e32 v162, 16, v178
	v_and_b32_e32 v163, 0xffff0000, v178
	v_lshlrev_b32_e32 v164, 16, v179
	v_and_b32_e32 v165, 0xffff0000, v179
	v_add_co_u32_e32 v166, vcc, s62, v154
	v_pk_add_f32 v[164:165], v[108:109], v[164:165]
	v_pk_add_f32 v[162:163], v[106:107], v[162:163]
	v_addc_co_u32_e32 v167, vcc, 0, v155, vcc
	global_store_dwordx4 v[166:167], v[162:165], off
	s_mov_b32 s62, 0x30000
	s_nop 0
;     __device__ __forceinline__ void operator()(const f32x4 (&acc)[2][2][4][2], const Unit& u, int wr, int wc, int fr, int fq) const {
;     ...
;             for (int m = 0; m < 4; ++m) {
;                 float* yo = yb + (size_t)(ai * HALF + m * 16) * 1024;
; #pragma unroll
;                 for (int bj = 0; bj < 2; ++bj) { float* p = yo + col0 + bj * HALF; const u32x4 w = xw[m][bj];
;                     *(f32x4*)p = (f32x4){__builtin_bit_cast(float, w.x << 16), __builtin_bit_cast(float, w.x & 0xffff0000u), __builtin_bit_cast(float, w.y << 16), __builtin_bit_cast(float, w.y & 0xffff0000u)} + acc[ai][bj][m][0];
;                     *(f32x4*)(p + 4) = (f32x4){__builtin_bit_cast(float, w.z << 16), __builtin_bit_cast(float, w.z & 0xffff0000u), __builtin_bit_cast(float, w.w << 16), __builtin_bit_cast(float, w.w & 0xffff0000u)} + acc[ai][bj][m][1]; }
	v_lshlrev_b32_e32 v162, 16, v180
	v_and_b32_e32 v163, 0xffff0000, v180
	v_lshlrev_b32_e32 v164, 16, v181
	v_and_b32_e32 v165, 0xffff0000, v181
	v_pk_add_f32 v[164:165], v[100:101], v[164:165]
	v_pk_add_f32 v[162:163], v[98:99], v[162:163]
	global_store_dwordx4 v[166:167], v[162:165], off offset:16
	s_nop 1
	v_lshlrev_b32_e32 v162, 16, v182
	v_and_b32_e32 v163, 0xffff0000, v182
	v_lshlrev_b32_e32 v164, 16, v183
	v_and_b32_e32 v165, 0xffff0000, v183
	v_pk_add_f32 v[164:165], v[80:81], v[164:165]
	v_pk_add_f32 v[162:163], v[78:79], v[162:163]
	global_store_dwordx4 v[166:167], v[162:165], off offset:512
	s_nop 1
	v_lshlrev_b32_e32 v162, 16, v184
	v_and_b32_e32 v163, 0xffff0000, v184
	v_lshlrev_b32_e32 v164, 16, v185
	v_and_b32_e32 v165, 0xffff0000, v185
	v_pk_add_f32 v[164:165], v[76:77], v[164:165]
	v_pk_add_f32 v[162:163], v[74:75], v[162:163]
	global_store_dwordx4 v[166:167], v[162:165], off offset:528
	v_add_co_u32_e32 v166, vcc, s62, v154
	s_nop 0
	v_lshlrev_b32_e32 v162, 16, v134
	v_and_b32_e32 v163, 0xffff0000, v134
	v_lshlrev_b32_e32 v134, 16, v135
	v_and_b32_e32 v135, 0xffff0000, v135
	v_pk_add_f32 v[164:165], v[92:93], v[134:135]
	v_lshlrev_b32_e32 v134, 16, v136
	v_and_b32_e32 v135, 0xffff0000, v136
	v_lshlrev_b32_e32 v136, 16, v137
	v_and_b32_e32 v137, 0xffff0000, v137
	v_addc_co_u32_e32 v167, vcc, 0, v155, vcc
	v_pk_add_f32 v[136:137], v[84:85], v[136:137]
	v_pk_add_f32 v[134:135], v[82:83], v[134:135]
	global_store_dwordx4 v[166:167], v[134:137], off offset:16
	v_pk_add_f32 v[162:163], v[90:91], v[162:163]
	global_store_dwordx4 v[166:167], v[162:165], off
	v_lshlrev_b32_e32 v134, 16, v130
	v_and_b32_e32 v135, 0xffff0000, v130
	v_lshlrev_b32_e32 v130, 16, v131
	v_and_b32_e32 v131, 0xffff0000, v131
	v_pk_add_f32 v[136:137], v[72:73], v[130:131]
	v_lshlrev_b32_e32 v130, 16, v132
	v_and_b32_e32 v131, 0xffff0000, v132
	v_lshlrev_b32_e32 v132, 16, v133
	v_and_b32_e32 v133, 0xffff0000, v133
	v_pk_add_f32 v[132:133], v[68:69], v[132:133]
	v_pk_add_f32 v[130:131], v[66:67], v[130:131]
	v_pk_add_f32 v[134:135], v[70:71], v[134:135]
	global_store_dwordx4 v[166:167], v[130:133], off offset:528
	global_store_dwordx4 v[166:167], v[134:137], off offset:512
	s_nop 0
	s_waitcnt vmcnt(23)
	v_lshlrev_b32_e32 v156, 16, v204
	v_and_b32_e32 v157, 0xffff0000, v204
	v_lshlrev_b32_e32 v134, 16, v205
	v_and_b32_e32 v135, 0xffff0000, v205
	v_pk_add_f32 v[188:189], v[64:65], v[134:135]
	v_pk_add_f32 v[186:187], v[62:63], v[156:157]
	v_add_co_u32_e32 v156, vcc, s79, v154
	v_lshlrev_b32_e32 v134, 16, v206
	v_and_b32_e32 v135, 0xffff0000, v206
	v_lshlrev_b32_e32 v136, 16, v207
	v_and_b32_e32 v137, 0xffff0000, v207
	v_addc_co_u32_e32 v157, vcc, 0, v155, vcc
	v_pk_add_f32 v[136:137], v[60:61], v[136:137]
	v_pk_add_f32 v[134:135], v[58:59], v[134:135]
	global_store_dwordx4 v[156:157], v[134:137], off offset:16
	global_store_dwordx4 v[156:157], v[186:189], off
	s_waitcnt vmcnt(24)
	v_lshlrev_b32_e32 v134, 16, v208
	v_and_b32_e32 v135, 0xffff0000, v208
	v_lshlrev_b32_e32 v136, 16, v209
	v_and_b32_e32 v137, 0xffff0000, v209
	v_pk_add_f32 v[136:137], v[48:49], v[136:137]
	v_pk_add_f32 v[134:135], v[46:47], v[134:135]
	global_store_dwordx4 v[156:157], v[134:137], off offset:512
	s_nop 1
	v_lshlrev_b32_e32 v134, 16, v210
	v_and_b32_e32 v135, 0xffff0000, v210
	v_lshlrev_b32_e32 v136, 16, v211
	v_and_b32_e32 v137, 0xffff0000, v211
	v_pk_add_f32 v[136:137], v[40:41], v[136:137]
	v_pk_add_f32 v[134:135], v[38:39], v[134:135]
	global_store_dwordx4 v[156:157], v[134:137], off offset:528
	v_add_co_u32_e32 v156, vcc, s80, v154
	s_waitcnt vmcnt(25)
;     __device__ __forceinline__ void operator()(const f32x4 (&acc)[2][2][4][2], const Unit& u, int wr, int wc, int fr, int fq) const {
;     ...
;             for (int m = 0; m < 4; ++m) {
;                 float* yo = yb + (size_t)(ai * HALF + m * 16) * 1024;
; #pragma unroll
;                 for (int bj = 0; bj < 2; ++bj) { float* p = yo + col0 + bj * HALF; const u32x4 w = xw[m][bj];
;                     *(f32x4*)p = (f32x4){__builtin_bit_cast(float, w.x << 16), __builtin_bit_cast(float, w.x & 0xffff0000u), __builtin_bit_cast(float, w.y << 16), __builtin_bit_cast(float, w.y & 0xffff0000u)} + acc[ai][bj][m][0];
;                     *(f32x4*)(p + 4) = (f32x4){__builtin_bit_cast(float, w.z << 16), __builtin_bit_cast(float, w.z & 0xffff0000u), __builtin_bit_cast(float, w.w << 16), __builtin_bit_cast(float, w.w & 0xffff0000u)} + acc[ai][bj][m][1]; }
	v_lshlrev_b32_e32 v134, 16, v212
	v_and_b32_e32 v135, 0xffff0000, v212
	v_lshlrev_b32_e32 v136, 16, v213
	v_and_b32_e32 v137, 0xffff0000, v213
	v_pk_add_f32 v[136:137], v[56:57], v[136:137]
	v_pk_add_f32 v[134:135], v[54:55], v[134:135]
	v_addc_co_u32_e32 v157, vcc, 0, v155, vcc
	global_store_dwordx4 v[156:157], v[134:137], off
	s_nop 1
	v_lshlrev_b32_e32 v134, 16, v214
	v_and_b32_e32 v135, 0xffff0000, v214
	v_lshlrev_b32_e32 v136, 16, v215
	v_and_b32_e32 v137, 0xffff0000, v215
	v_pk_add_f32 v[136:137], v[52:53], v[136:137]
	v_pk_add_f32 v[134:135], v[50:51], v[134:135]
	global_store_dwordx4 v[156:157], v[134:137], off offset:16
	s_waitcnt vmcnt(26)
	s_nop 0
	v_lshlrev_b32_e32 v134, 16, v216
	v_and_b32_e32 v135, 0xffff0000, v216
	v_lshlrev_b32_e32 v136, 16, v217
	v_and_b32_e32 v137, 0xffff0000, v217
	v_pk_add_f32 v[136:137], v[32:33], v[136:137]
	v_pk_add_f32 v[134:135], v[30:31], v[134:135]
	global_store_dwordx4 v[156:157], v[134:137], off offset:512
	s_nop 1
	v_lshlrev_b32_e32 v134, 16, v218
	v_and_b32_e32 v135, 0xffff0000, v218
	v_lshlrev_b32_e32 v136, 16, v219
	v_and_b32_e32 v137, 0xffff0000, v219
	v_pk_add_f32 v[136:137], v[24:25], v[136:137]
	v_pk_add_f32 v[134:135], v[22:23], v[134:135]
	global_store_dwordx4 v[156:157], v[134:137], off offset:528
	v_add_co_u32_e32 v156, vcc, s81, v154
	s_waitcnt vmcnt(27)
	v_lshlrev_b32_e32 v134, 16, v220
	v_and_b32_e32 v135, 0xffff0000, v220
	v_lshlrev_b32_e32 v136, 16, v221
	v_and_b32_e32 v137, 0xffff0000, v221
	v_pk_add_f32 v[136:137], v[44:45], v[136:137]
	v_pk_add_f32 v[134:135], v[42:43], v[134:135]
	v_addc_co_u32_e32 v157, vcc, 0, v155, vcc
	global_store_dwordx4 v[156:157], v[134:137], off
	v_add_co_u32_e32 v154, vcc, s82, v154
	s_nop 0
	v_lshlrev_b32_e32 v134, 16, v222
	v_and_b32_e32 v135, 0xffff0000, v222
	v_lshlrev_b32_e32 v136, 16, v223
	v_and_b32_e32 v137, 0xffff0000, v223
	v_pk_add_f32 v[136:137], v[36:37], v[136:137]
	v_pk_add_f32 v[134:135], v[34:35], v[134:135]
	global_store_dwordx4 v[156:157], v[134:137], off offset:16
	v_addc_co_u32_e32 v155, vcc, 0, v155, vcc
	s_waitcnt vmcnt(28)
	v_lshlrev_b32_e32 v134, 16, v224
	v_and_b32_e32 v135, 0xffff0000, v224
	v_lshlrev_b32_e32 v136, 16, v225
	v_and_b32_e32 v137, 0xffff0000, v225
	v_pk_add_f32 v[136:137], v[16:17], v[136:137]
	v_pk_add_f32 v[134:135], v[14:15], v[134:135]
	global_store_dwordx4 v[156:157], v[134:137], off offset:512
	s_nop 1
	v_lshlrev_b32_e32 v134, 16, v226
	v_and_b32_e32 v135, 0xffff0000, v226
	v_lshlrev_b32_e32 v136, 16, v227
	v_and_b32_e32 v137, 0xffff0000, v227
	v_pk_add_f32 v[136:137], v[12:13], v[136:137]
	v_pk_add_f32 v[134:135], v[10:11], v[134:135]
	global_store_dwordx4 v[156:157], v[134:137], off offset:528
	s_waitcnt vmcnt(29)
	s_nop 0
	v_lshlrev_b32_e32 v134, 16, v228
	v_and_b32_e32 v135, 0xffff0000, v228
	v_lshlrev_b32_e32 v136, 16, v229
	v_and_b32_e32 v137, 0xffff0000, v229
	v_pk_add_f32 v[136:137], v[28:29], v[136:137]
	v_pk_add_f32 v[134:135], v[26:27], v[134:135]
	global_store_dwordx4 v[154:155], v[134:137], off
	s_nop 1
	v_lshlrev_b32_e32 v134, 16, v230
	v_and_b32_e32 v135, 0xffff0000, v230
	v_lshlrev_b32_e32 v136, 16, v231
	v_and_b32_e32 v137, 0xffff0000, v231
	v_pk_add_f32 v[136:137], v[20:21], v[136:137]
	v_pk_add_f32 v[134:135], v[18:19], v[134:135]
	global_store_dwordx4 v[154:155], v[134:137], off offset:16
	s_waitcnt vmcnt(30)
	s_nop 0
	v_lshlrev_b32_e32 v134, 16, v232
	v_and_b32_e32 v135, 0xffff0000, v232
	v_lshlrev_b32_e32 v130, 16, v233
	v_and_b32_e32 v131, 0xffff0000, v233
	v_pk_add_f32 v[136:137], v[8:9], v[130:131]
	v_lshlrev_b32_e32 v130, 16, v234
	v_and_b32_e32 v131, 0xffff0000, v234
	v_lshlrev_b32_e32 v132, 16, v235
	v_and_b32_e32 v133, 0xffff0000, v235
	v_pk_add_f32 v[134:135], v[6:7], v[134:135]
	v_pk_add_f32 v[132:133], v[4:5], v[132:133]
	v_pk_add_f32 v[130:131], v[2:3], v[130:131]
	global_store_dwordx4 v[154:155], v[134:137], off offset:512
	global_store_dwordx4 v[154:155], v[130:133], off offset:528
	s_cbranch_execz .LBB0_1184
